# attention causal-mask section: 32 bias-table reads batched and applied with v_cndmask (no per-element exec branches), on the zero64 kernel
# speedup vs baseline: 1.0054x; 1.0027x over previous
.LBB0_1084:
	ds_read_b128 v[68:71], v234
	ds_read_b128 v[100:103], v234 offset:32
	ds_read_b128 v[72:75], v234 offset:8704
	ds_read_b128 v[104:107], v234 offset:8736
	ds_read_b128 v[108:111], v234 offset:64
	ds_read_b128 v[112:115], v234 offset:96
	ds_read_b128 v[116:119], v234 offset:8768
	ds_read_b128 v[120:123], v234 offset:8800
	s_waitcnt vmcnt(1) lgkmcnt(0)
	v_mfma_f32_32x32x16_bf16 v[84:99], v[68:71], v[140:143], 0
	ds_read_b64_tr_b16 v[176:177], v235 offset:17408
	ds_read_b64_tr_b16 v[172:173], v235 offset:17472
	ds_read_b64_tr_b16 v[168:169], v235 offset:17536
	ds_read_b64_tr_b16 v[164:165], v235 offset:17600
	ds_read_b64_tr_b16 v[178:179], v235 offset:19968
	ds_read_b64_tr_b16 v[174:175], v235 offset:20032
	ds_read_b64_tr_b16 v[170:171], v235 offset:20096
	ds_read_b64_tr_b16 v[166:167], v235 offset:20160
	v_mfma_f32_32x32x16_bf16 v[68:83], v[72:75], v[140:143], 0
	v_mfma_f32_32x32x16_bf16 v[84:99], v[100:103], v[132:135], v[84:99]
	v_mfma_f32_32x32x16_bf16 v[68:83], v[104:107], v[132:135], v[68:83]
	v_mfma_f32_32x32x16_bf16 v[84:99], v[108:111], v[136:139], v[84:99]
	v_mfma_f32_32x32x16_bf16 v[68:83], v[116:119], v[136:139], v[68:83]
	s_waitcnt vmcnt(0)
	v_mfma_f32_32x32x16_bf16 v[84:99], v[112:115], v[144:147], v[84:99]
	v_mfma_f32_32x32x16_bf16 v[68:83], v[120:123], v[144:147], v[68:83]
	s_cmp_lt_i32 s52, s50
	s_cbranch_scc1 .LBB0_1150
	s_mov_b32 s98, 0x12800
	s_mov_b32 s99, 0x12780
	v_mov_b32_e32 v246, 0xf149f2ca
	v_add_u32_e32 v243, 0, v67
	v_min_u32_e32 v244, 0x7f, v243
	v_min_u32_e32 v245, 0x9f, v243
	v_lshl_add_u32 v244, v244, 2, s98
	v_lshl_add_u32 v245, v245, 2, s99
	ds_read_b32 v116, v244
	ds_read_b32 v100, v245
	v_add_u32_e32 v243, -1, v67
	v_min_u32_e32 v244, 0x7f, v243
	v_min_u32_e32 v245, 0x9f, v243
	v_lshl_add_u32 v244, v244, 2, s98
	v_lshl_add_u32 v245, v245, 2, s99
	ds_read_b32 v117, v244
	ds_read_b32 v101, v245
	v_add_u32_e32 v243, -2, v67
	v_min_u32_e32 v244, 0x7f, v243
	v_min_u32_e32 v245, 0x9f, v243
	v_lshl_add_u32 v244, v244, 2, s98
	v_lshl_add_u32 v245, v245, 2, s99
	ds_read_b32 v118, v244
	ds_read_b32 v102, v245
	v_add_u32_e32 v243, -3, v67
	v_min_u32_e32 v244, 0x7f, v243
	v_min_u32_e32 v245, 0x9f, v243
	v_lshl_add_u32 v244, v244, 2, s98
	v_lshl_add_u32 v245, v245, 2, s99
	ds_read_b32 v119, v244
	ds_read_b32 v103, v245
	v_add_u32_e32 v243, -8, v67
	v_min_u32_e32 v244, 0x7f, v243
	v_min_u32_e32 v245, 0x9f, v243
	v_lshl_add_u32 v244, v244, 2, s98
	v_lshl_add_u32 v245, v245, 2, s99
	ds_read_b32 v120, v244
	ds_read_b32 v104, v245
	v_add_u32_e32 v243, -9, v67
	v_min_u32_e32 v244, 0x7f, v243
	v_min_u32_e32 v245, 0x9f, v243
	v_lshl_add_u32 v244, v244, 2, s98
	v_lshl_add_u32 v245, v245, 2, s99
	ds_read_b32 v121, v244
	ds_read_b32 v105, v245
	v_add_u32_e32 v243, -10, v67
	v_min_u32_e32 v244, 0x7f, v243
	v_min_u32_e32 v245, 0x9f, v243
	v_lshl_add_u32 v244, v244, 2, s98
	v_lshl_add_u32 v245, v245, 2, s99
	ds_read_b32 v122, v244
	ds_read_b32 v106, v245
	v_add_u32_e32 v243, -11, v67
	v_min_u32_e32 v244, 0x7f, v243
	v_min_u32_e32 v245, 0x9f, v243
	v_lshl_add_u32 v244, v244, 2, s98
	v_lshl_add_u32 v245, v245, 2, s99
	ds_read_b32 v123, v244
	ds_read_b32 v107, v245
	v_add_u32_e32 v243, -16, v67
	v_min_u32_e32 v244, 0x7f, v243
	v_min_u32_e32 v245, 0x9f, v243
	v_lshl_add_u32 v244, v244, 2, s98
	v_lshl_add_u32 v245, v245, 2, s99
	ds_read_b32 v124, v244
	ds_read_b32 v108, v245
	v_add_u32_e32 v243, 0xffffffef, v67
	v_min_u32_e32 v244, 0x7f, v243
	v_min_u32_e32 v245, 0x9f, v243
	v_lshl_add_u32 v244, v244, 2, s98
	v_lshl_add_u32 v245, v245, 2, s99
	ds_read_b32 v125, v244
	ds_read_b32 v109, v245
	v_add_u32_e32 v243, 0xffffffee, v67
	v_min_u32_e32 v244, 0x7f, v243
	v_min_u32_e32 v245, 0x9f, v243
	v_lshl_add_u32 v244, v244, 2, s98
	v_lshl_add_u32 v245, v245, 2, s99
	ds_read_b32 v126, v244
	ds_read_b32 v110, v245
	v_add_u32_e32 v243, 0xffffffed, v67
	v_min_u32_e32 v244, 0x7f, v243
	v_min_u32_e32 v245, 0x9f, v243
	v_lshl_add_u32 v244, v244, 2, s98
	v_lshl_add_u32 v245, v245, 2, s99
	ds_read_b32 v127, v244
	ds_read_b32 v111, v245
	v_add_u32_e32 v243, 0xffffffe8, v67
	v_min_u32_e32 v244, 0x7f, v243
	v_min_u32_e32 v245, 0x9f, v243
	v_lshl_add_u32 v244, v244, 2, s98
	v_lshl_add_u32 v245, v245, 2, s99
	ds_read_b32 v128, v244
	ds_read_b32 v112, v245
	v_add_u32_e32 v243, 0xffffffe7, v67
	v_min_u32_e32 v244, 0x7f, v243
	v_min_u32_e32 v245, 0x9f, v243
	v_lshl_add_u32 v244, v244, 2, s98
	v_lshl_add_u32 v245, v245, 2, s99
	ds_read_b32 v129, v244
	ds_read_b32 v113, v245
	v_add_u32_e32 v243, 0xffffffe6, v67
	v_min_u32_e32 v244, 0x7f, v243
	v_min_u32_e32 v245, 0x9f, v243
	v_lshl_add_u32 v244, v244, 2, s98
	v_lshl_add_u32 v245, v245, 2, s99
	ds_read_b32 v130, v244
	ds_read_b32 v114, v245
	v_add_u32_e32 v243, 0xffffffe5, v67
	v_min_u32_e32 v244, 0x7f, v243
	v_min_u32_e32 v245, 0x9f, v243
	v_lshl_add_u32 v244, v244, 2, s98
	v_lshl_add_u32 v245, v245, 2, s99
	ds_read_b32 v131, v244
	ds_read_b32 v115, v245
	s_waitcnt lgkmcnt(0)
	v_add_u32_e32 v243, 0, v67
	v_add_f32_e32 v116, v84, v116
	v_cmp_lt_i32_e32 vcc, -1, v243
	v_cndmask_b32_e32 v116, v246, v116, vcc
	v_add_f32_e32 v100, v68, v100
	v_cmp_lt_i32_e32 vcc, 31, v243
	v_cndmask_b32_e32 v100, v246, v100, vcc
	v_add_u32_e32 v243, -1, v67
	v_add_f32_e32 v117, v85, v117
	v_cmp_lt_i32_e32 vcc, -1, v243
	v_cndmask_b32_e32 v117, v246, v117, vcc
	v_add_f32_e32 v101, v69, v101
	v_cmp_lt_i32_e32 vcc, 31, v243
	v_cndmask_b32_e32 v101, v246, v101, vcc
	v_add_u32_e32 v243, -2, v67
	v_add_f32_e32 v118, v86, v118
	v_cmp_lt_i32_e32 vcc, -1, v243
	v_cndmask_b32_e32 v118, v246, v118, vcc
	v_add_f32_e32 v102, v70, v102
	v_cmp_lt_i32_e32 vcc, 31, v243
	v_cndmask_b32_e32 v102, v246, v102, vcc
	v_add_u32_e32 v243, -3, v67
	v_add_f32_e32 v119, v87, v119
	v_cmp_lt_i32_e32 vcc, -1, v243
	v_cndmask_b32_e32 v119, v246, v119, vcc
	v_add_f32_e32 v103, v71, v103
	v_cmp_lt_i32_e32 vcc, 31, v243
	v_cndmask_b32_e32 v103, v246, v103, vcc
	v_add_u32_e32 v243, -8, v67
	v_add_f32_e32 v120, v88, v120
	v_cmp_lt_i32_e32 vcc, -1, v243
	v_cndmask_b32_e32 v120, v246, v120, vcc
	v_add_f32_e32 v104, v72, v104
	v_cmp_lt_i32_e32 vcc, 31, v243
	v_cndmask_b32_e32 v104, v246, v104, vcc
	v_add_u32_e32 v243, -9, v67
	v_add_f32_e32 v121, v89, v121
	v_cmp_lt_i32_e32 vcc, -1, v243
	v_cndmask_b32_e32 v121, v246, v121, vcc
	v_add_f32_e32 v105, v73, v105
	v_cmp_lt_i32_e32 vcc, 31, v243
	v_cndmask_b32_e32 v105, v246, v105, vcc
	v_add_u32_e32 v243, -10, v67
	v_add_f32_e32 v122, v90, v122
	v_cmp_lt_i32_e32 vcc, -1, v243
	v_cndmask_b32_e32 v122, v246, v122, vcc
	v_add_f32_e32 v106, v74, v106
	v_cmp_lt_i32_e32 vcc, 31, v243
	v_cndmask_b32_e32 v106, v246, v106, vcc
	v_add_u32_e32 v243, -11, v67
	v_add_f32_e32 v123, v91, v123
	v_cmp_lt_i32_e32 vcc, -1, v243
	v_cndmask_b32_e32 v123, v246, v123, vcc
	v_add_f32_e32 v107, v75, v107
	v_cmp_lt_i32_e32 vcc, 31, v243
	v_cndmask_b32_e32 v107, v246, v107, vcc
	v_add_u32_e32 v243, -16, v67
	v_add_f32_e32 v124, v92, v124
	v_cmp_lt_i32_e32 vcc, -1, v243
	v_cndmask_b32_e32 v124, v246, v124, vcc
	v_add_f32_e32 v108, v76, v108
	v_cmp_lt_i32_e32 vcc, 31, v243
	v_cndmask_b32_e32 v108, v246, v108, vcc
	v_add_u32_e32 v243, 0xffffffef, v67
	v_add_f32_e32 v125, v93, v125
	v_cmp_lt_i32_e32 vcc, -1, v243
	v_cndmask_b32_e32 v125, v246, v125, vcc
	v_add_f32_e32 v109, v77, v109
	v_cmp_lt_i32_e32 vcc, 31, v243
	v_cndmask_b32_e32 v109, v246, v109, vcc
	v_add_u32_e32 v243, 0xffffffee, v67
	v_add_f32_e32 v126, v94, v126
	v_cmp_lt_i32_e32 vcc, -1, v243
	v_cndmask_b32_e32 v126, v246, v126, vcc
	v_add_f32_e32 v110, v78, v110
	v_cmp_lt_i32_e32 vcc, 31, v243
	v_cndmask_b32_e32 v110, v246, v110, vcc
	v_add_u32_e32 v243, 0xffffffed, v67
	v_add_f32_e32 v127, v95, v127
	v_cmp_lt_i32_e32 vcc, -1, v243
	v_cndmask_b32_e32 v127, v246, v127, vcc
	v_add_f32_e32 v111, v79, v111
	v_cmp_lt_i32_e32 vcc, 31, v243
	v_cndmask_b32_e32 v111, v246, v111, vcc
	v_add_u32_e32 v243, 0xffffffe8, v67
	v_add_f32_e32 v128, v96, v128
	v_cmp_lt_i32_e32 vcc, -1, v243
	v_cndmask_b32_e32 v128, v246, v128, vcc
	v_add_f32_e32 v112, v80, v112
	v_cmp_lt_i32_e32 vcc, 31, v243
	v_cndmask_b32_e32 v112, v246, v112, vcc
	v_add_u32_e32 v243, 0xffffffe7, v67
	v_add_f32_e32 v129, v97, v129
	v_cmp_lt_i32_e32 vcc, -1, v243
	v_cndmask_b32_e32 v129, v246, v129, vcc
	v_add_f32_e32 v113, v81, v113
	v_cmp_lt_i32_e32 vcc, 31, v243
	v_cndmask_b32_e32 v113, v246, v113, vcc
	v_add_u32_e32 v243, 0xffffffe6, v67
	v_add_f32_e32 v130, v98, v130
	v_cmp_lt_i32_e32 vcc, -1, v243
	v_cndmask_b32_e32 v130, v246, v130, vcc
	v_add_f32_e32 v114, v82, v114
	v_cmp_lt_i32_e32 vcc, 31, v243
	v_cndmask_b32_e32 v114, v246, v114, vcc
	v_add_u32_e32 v243, 0xffffffe5, v67
	v_add_f32_e32 v131, v99, v131
	v_cmp_lt_i32_e32 vcc, -1, v243
	v_cndmask_b32_e32 v131, v246, v131, vcc
	v_add_f32_e32 v115, v83, v115
	v_cmp_lt_i32_e32 vcc, 31, v243
	v_cndmask_b32_e32 v115, v246, v115, vcc

.LBB0_1156:
	ds_read_b128 v[68:71], v234 offset:37888
	ds_read_b128 v[100:103], v234 offset:37920
	ds_read_b128 v[72:75], v234 offset:46592
	ds_read_b128 v[104:107], v234 offset:46624
	ds_read_b128 v[108:111], v234 offset:37952
	ds_read_b128 v[112:115], v234 offset:37984
	ds_read_b128 v[116:119], v234 offset:46656
	ds_read_b128 v[120:123], v234 offset:46688
	s_add_i32 s12, s51, -2
	s_waitcnt lgkmcnt(7)
	v_mfma_f32_32x32x16_bf16 v[84:99], v[68:71], v[140:143], 0
	ds_read_b64_tr_b16 v[176:177], v235 offset:55296
	ds_read_b64_tr_b16 v[172:173], v235 offset:55360
	ds_read_b64_tr_b16 v[168:169], v235 offset:55424
	ds_read_b64_tr_b16 v[164:165], v235 offset:55488
	ds_read_b64_tr_b16 v[178:179], v235 offset:57856
	ds_read_b64_tr_b16 v[174:175], v235 offset:57920
	ds_read_b64_tr_b16 v[170:171], v235 offset:57984
	ds_read_b64_tr_b16 v[166:167], v235 offset:58048
	s_waitcnt lgkmcnt(13)
	v_mfma_f32_32x32x16_bf16 v[68:83], v[72:75], v[140:143], 0
	v_mfma_f32_32x32x16_bf16 v[84:99], v[100:103], v[132:135], v[84:99]
	s_waitcnt lgkmcnt(12)
	v_mfma_f32_32x32x16_bf16 v[68:83], v[104:107], v[132:135], v[68:83]
	s_waitcnt lgkmcnt(11)
	v_mfma_f32_32x32x16_bf16 v[84:99], v[108:111], v[136:139], v[84:99]
	s_waitcnt lgkmcnt(9)
	v_mfma_f32_32x32x16_bf16 v[68:83], v[116:119], v[136:139], v[68:83]
	v_mfma_f32_32x32x16_bf16 v[84:99], v[112:115], v[144:147], v[84:99]
	s_waitcnt lgkmcnt(8)
	v_mfma_f32_32x32x16_bf16 v[68:83], v[120:123], v[144:147], v[68:83]
	s_cmp_lt_i32 s12, s50
	s_cbranch_scc1 .LBB0_1222
	s_mov_b32 s98, 0x12800
	s_mov_b32 s99, 0x12780
	v_mov_b32_e32 v246, 0xf149f2ca
	v_add_u32_e32 v243, 0xffffffc0, v67
	v_min_u32_e32 v244, 0x7f, v243
	v_min_u32_e32 v245, 0x9f, v243
	v_lshl_add_u32 v244, v244, 2, s98
	v_lshl_add_u32 v245, v245, 2, s99
	ds_read_b32 v116, v244
	ds_read_b32 v100, v245
	v_add_u32_e32 v243, 0xffffffbf, v67
	v_min_u32_e32 v244, 0x7f, v243
	v_min_u32_e32 v245, 0x9f, v243
	v_lshl_add_u32 v244, v244, 2, s98
	v_lshl_add_u32 v245, v245, 2, s99
	ds_read_b32 v117, v244
	ds_read_b32 v101, v245
	v_add_u32_e32 v243, 0xffffffbe, v67
	v_min_u32_e32 v244, 0x7f, v243
	v_min_u32_e32 v245, 0x9f, v243
	v_lshl_add_u32 v244, v244, 2, s98
	v_lshl_add_u32 v245, v245, 2, s99
	ds_read_b32 v118, v244
	ds_read_b32 v102, v245
	v_add_u32_e32 v243, 0xffffffbd, v67
	v_min_u32_e32 v244, 0x7f, v243
	v_min_u32_e32 v245, 0x9f, v243
	v_lshl_add_u32 v244, v244, 2, s98
	v_lshl_add_u32 v245, v245, 2, s99
	ds_read_b32 v119, v244
	ds_read_b32 v103, v245
	v_add_u32_e32 v243, 0xffffffb8, v67
	v_min_u32_e32 v244, 0x7f, v243
	v_min_u32_e32 v245, 0x9f, v243
	v_lshl_add_u32 v244, v244, 2, s98
	v_lshl_add_u32 v245, v245, 2, s99
	ds_read_b32 v120, v244
	ds_read_b32 v104, v245
	v_add_u32_e32 v243, 0xffffffb7, v67
	v_min_u32_e32 v244, 0x7f, v243
	v_min_u32_e32 v245, 0x9f, v243
	v_lshl_add_u32 v244, v244, 2, s98
	v_lshl_add_u32 v245, v245, 2, s99
	ds_read_b32 v121, v244
	ds_read_b32 v105, v245
	v_add_u32_e32 v243, 0xffffffb6, v67
	v_min_u32_e32 v244, 0x7f, v243
	v_min_u32_e32 v245, 0x9f, v243
	v_lshl_add_u32 v244, v244, 2, s98
	v_lshl_add_u32 v245, v245, 2, s99
	ds_read_b32 v122, v244
	ds_read_b32 v106, v245
	v_add_u32_e32 v243, 0xffffffb5, v67
	v_min_u32_e32 v244, 0x7f, v243
	v_min_u32_e32 v245, 0x9f, v243
	v_lshl_add_u32 v244, v244, 2, s98
	v_lshl_add_u32 v245, v245, 2, s99
	ds_read_b32 v123, v244
	ds_read_b32 v107, v245
	v_add_u32_e32 v243, 0xffffffb0, v67
	v_min_u32_e32 v244, 0x7f, v243
	v_min_u32_e32 v245, 0x9f, v243
	v_lshl_add_u32 v244, v244, 2, s98
	v_lshl_add_u32 v245, v245, 2, s99
	ds_read_b32 v124, v244
	ds_read_b32 v108, v245
	v_add_u32_e32 v243, 0xffffffaf, v67
	v_min_u32_e32 v244, 0x7f, v243
	v_min_u32_e32 v245, 0x9f, v243
	v_lshl_add_u32 v244, v244, 2, s98
	v_lshl_add_u32 v245, v245, 2, s99
	ds_read_b32 v125, v244
	ds_read_b32 v109, v245
	v_add_u32_e32 v243, 0xffffffae, v67
	v_min_u32_e32 v244, 0x7f, v243
	v_min_u32_e32 v245, 0x9f, v243
	v_lshl_add_u32 v244, v244, 2, s98
	v_lshl_add_u32 v245, v245, 2, s99
	ds_read_b32 v126, v244
	ds_read_b32 v110, v245
	v_add_u32_e32 v243, 0xffffffad, v67
	v_min_u32_e32 v244, 0x7f, v243
	v_min_u32_e32 v245, 0x9f, v243
	v_lshl_add_u32 v244, v244, 2, s98
	v_lshl_add_u32 v245, v245, 2, s99
	ds_read_b32 v127, v244
	ds_read_b32 v111, v245
	v_add_u32_e32 v243, 0xffffffa8, v67
	v_min_u32_e32 v244, 0x7f, v243
	v_min_u32_e32 v245, 0x9f, v243
	v_lshl_add_u32 v244, v244, 2, s98
	v_lshl_add_u32 v245, v245, 2, s99
	ds_read_b32 v128, v244
	ds_read_b32 v112, v245
	v_add_u32_e32 v243, 0xffffffa7, v67
	v_min_u32_e32 v244, 0x7f, v243
	v_min_u32_e32 v245, 0x9f, v243
	v_lshl_add_u32 v244, v244, 2, s98
	v_lshl_add_u32 v245, v245, 2, s99
	ds_read_b32 v129, v244
	ds_read_b32 v113, v245
	v_add_u32_e32 v243, 0xffffffa6, v67
	v_min_u32_e32 v244, 0x7f, v243
	v_min_u32_e32 v245, 0x9f, v243
	v_lshl_add_u32 v244, v244, 2, s98
	v_lshl_add_u32 v245, v245, 2, s99
	ds_read_b32 v130, v244
	ds_read_b32 v114, v245
	v_add_u32_e32 v243, 0xffffffa5, v67
	v_min_u32_e32 v244, 0x7f, v243
	v_min_u32_e32 v245, 0x9f, v243
	v_lshl_add_u32 v244, v244, 2, s98
	v_lshl_add_u32 v245, v245, 2, s99
	ds_read_b32 v131, v244
	ds_read_b32 v115, v245
	s_waitcnt lgkmcnt(0)
	v_add_u32_e32 v243, 0xffffffc0, v67
	v_add_f32_e32 v116, v84, v116
	v_cmp_lt_i32_e32 vcc, -1, v243
	v_cndmask_b32_e32 v116, v246, v116, vcc
	v_add_f32_e32 v100, v68, v100
	v_cmp_lt_i32_e32 vcc, 31, v243
	v_cndmask_b32_e32 v100, v246, v100, vcc
	v_add_u32_e32 v243, 0xffffffbf, v67
	v_add_f32_e32 v117, v85, v117
	v_cmp_lt_i32_e32 vcc, -1, v243
	v_cndmask_b32_e32 v117, v246, v117, vcc
	v_add_f32_e32 v101, v69, v101
	v_cmp_lt_i32_e32 vcc, 31, v243
	v_cndmask_b32_e32 v101, v246, v101, vcc
	v_add_u32_e32 v243, 0xffffffbe, v67
	v_add_f32_e32 v118, v86, v118
	v_cmp_lt_i32_e32 vcc, -1, v243
	v_cndmask_b32_e32 v118, v246, v118, vcc
	v_add_f32_e32 v102, v70, v102
	v_cmp_lt_i32_e32 vcc, 31, v243
	v_cndmask_b32_e32 v102, v246, v102, vcc
	v_add_u32_e32 v243, 0xffffffbd, v67
	v_add_f32_e32 v119, v87, v119
	v_cmp_lt_i32_e32 vcc, -1, v243
	v_cndmask_b32_e32 v119, v246, v119, vcc
	v_add_f32_e32 v103, v71, v103
	v_cmp_lt_i32_e32 vcc, 31, v243
	v_cndmask_b32_e32 v103, v246, v103, vcc
	v_add_u32_e32 v243, 0xffffffb8, v67
	v_add_f32_e32 v120, v88, v120
	v_cmp_lt_i32_e32 vcc, -1, v243
	v_cndmask_b32_e32 v120, v246, v120, vcc
	v_add_f32_e32 v104, v72, v104
	v_cmp_lt_i32_e32 vcc, 31, v243
	v_cndmask_b32_e32 v104, v246, v104, vcc
	v_add_u32_e32 v243, 0xffffffb7, v67
	v_add_f32_e32 v121, v89, v121
	v_cmp_lt_i32_e32 vcc, -1, v243
	v_cndmask_b32_e32 v121, v246, v121, vcc
	v_add_f32_e32 v105, v73, v105
	v_cmp_lt_i32_e32 vcc, 31, v243
	v_cndmask_b32_e32 v105, v246, v105, vcc
	v_add_u32_e32 v243, 0xffffffb6, v67
	v_add_f32_e32 v122, v90, v122
	v_cmp_lt_i32_e32 vcc, -1, v243
	v_cndmask_b32_e32 v122, v246, v122, vcc
	v_add_f32_e32 v106, v74, v106
	v_cmp_lt_i32_e32 vcc, 31, v243
	v_cndmask_b32_e32 v106, v246, v106, vcc
	v_add_u32_e32 v243, 0xffffffb5, v67
	v_add_f32_e32 v123, v91, v123
	v_cmp_lt_i32_e32 vcc, -1, v243
	v_cndmask_b32_e32 v123, v246, v123, vcc
	v_add_f32_e32 v107, v75, v107
	v_cmp_lt_i32_e32 vcc, 31, v243
	v_cndmask_b32_e32 v107, v246, v107, vcc
	v_add_u32_e32 v243, 0xffffffb0, v67
	v_add_f32_e32 v124, v92, v124
	v_cmp_lt_i32_e32 vcc, -1, v243
	v_cndmask_b32_e32 v124, v246, v124, vcc
	v_add_f32_e32 v108, v76, v108
	v_cmp_lt_i32_e32 vcc, 31, v243
	v_cndmask_b32_e32 v108, v246, v108, vcc
	v_add_u32_e32 v243, 0xffffffaf, v67
	v_add_f32_e32 v125, v93, v125
	v_cmp_lt_i32_e32 vcc, -1, v243
	v_cndmask_b32_e32 v125, v246, v125, vcc
	v_add_f32_e32 v109, v77, v109
	v_cmp_lt_i32_e32 vcc, 31, v243
	v_cndmask_b32_e32 v109, v246, v109, vcc
	v_add_u32_e32 v243, 0xffffffae, v67
	v_add_f32_e32 v126, v94, v126
	v_cmp_lt_i32_e32 vcc, -1, v243
	v_cndmask_b32_e32 v126, v246, v126, vcc
	v_add_f32_e32 v110, v78, v110
	v_cmp_lt_i32_e32 vcc, 31, v243
	v_cndmask_b32_e32 v110, v246, v110, vcc
	v_add_u32_e32 v243, 0xffffffad, v67
	v_add_f32_e32 v127, v95, v127
	v_cmp_lt_i32_e32 vcc, -1, v243
	v_cndmask_b32_e32 v127, v246, v127, vcc
	v_add_f32_e32 v111, v79, v111
	v_cmp_lt_i32_e32 vcc, 31, v243
	v_cndmask_b32_e32 v111, v246, v111, vcc
	v_add_u32_e32 v243, 0xffffffa8, v67
	v_add_f32_e32 v128, v96, v128
	v_cmp_lt_i32_e32 vcc, -1, v243
	v_cndmask_b32_e32 v128, v246, v128, vcc
	v_add_f32_e32 v112, v80, v112
	v_cmp_lt_i32_e32 vcc, 31, v243
	v_cndmask_b32_e32 v112, v246, v112, vcc
	v_add_u32_e32 v243, 0xffffffa7, v67
	v_add_f32_e32 v129, v97, v129
	v_cmp_lt_i32_e32 vcc, -1, v243
	v_cndmask_b32_e32 v129, v246, v129, vcc
	v_add_f32_e32 v113, v81, v113
	v_cmp_lt_i32_e32 vcc, 31, v243
	v_cndmask_b32_e32 v113, v246, v113, vcc
	v_add_u32_e32 v243, 0xffffffa6, v67
	v_add_f32_e32 v130, v98, v130
	v_cmp_lt_i32_e32 vcc, -1, v243
	v_cndmask_b32_e32 v130, v246, v130, vcc
	v_add_f32_e32 v114, v82, v114
	v_cmp_lt_i32_e32 vcc, 31, v243
	v_cndmask_b32_e32 v114, v246, v114, vcc
	v_add_u32_e32 v243, 0xffffffa5, v67
	v_add_f32_e32 v131, v99, v131
	v_cmp_lt_i32_e32 vcc, -1, v243
	v_cndmask_b32_e32 v131, v246, v131, vcc
	v_add_f32_e32 v115, v83, v115
	v_cmp_lt_i32_e32 vcc, 31, v243
	v_cndmask_b32_e32 v115, v246, v115, vcc

.LBB0_2344:
	ds_read_b128 v[68:71], v234
	ds_read_b128 v[100:103], v234 offset:32
	ds_read_b128 v[72:75], v234 offset:8704
	ds_read_b128 v[104:107], v234 offset:8736
	ds_read_b128 v[108:111], v234 offset:64
	ds_read_b128 v[112:115], v234 offset:96
	ds_read_b128 v[116:119], v234 offset:8768
	ds_read_b128 v[120:123], v234 offset:8800
	s_waitcnt vmcnt(1) lgkmcnt(0)
	v_mfma_f32_32x32x16_bf16 v[84:99], v[68:71], v[140:143], 0
	ds_read_b64_tr_b16 v[176:177], v235 offset:17408
	ds_read_b64_tr_b16 v[172:173], v235 offset:17472
	ds_read_b64_tr_b16 v[168:169], v235 offset:17536
	ds_read_b64_tr_b16 v[164:165], v235 offset:17600
	ds_read_b64_tr_b16 v[178:179], v235 offset:19968
	ds_read_b64_tr_b16 v[174:175], v235 offset:20032
	ds_read_b64_tr_b16 v[170:171], v235 offset:20096
	ds_read_b64_tr_b16 v[166:167], v235 offset:20160
	v_mfma_f32_32x32x16_bf16 v[68:83], v[72:75], v[140:143], 0
	v_mfma_f32_32x32x16_bf16 v[84:99], v[100:103], v[132:135], v[84:99]
	v_mfma_f32_32x32x16_bf16 v[68:83], v[104:107], v[132:135], v[68:83]
	v_mfma_f32_32x32x16_bf16 v[84:99], v[108:111], v[136:139], v[84:99]
	v_mfma_f32_32x32x16_bf16 v[68:83], v[116:119], v[136:139], v[68:83]
	s_waitcnt vmcnt(0)
	v_mfma_f32_32x32x16_bf16 v[84:99], v[112:115], v[144:147], v[84:99]
	v_mfma_f32_32x32x16_bf16 v[68:83], v[120:123], v[144:147], v[68:83]
	s_cmp_lt_i32 s69, s67
	s_cbranch_scc1 .LBB0_2410
	s_mov_b32 s98, 0x12800
	s_mov_b32 s99, 0x12780
	v_mov_b32_e32 v246, 0xf149f2ca
	v_add_u32_e32 v243, 0, v67
	v_min_u32_e32 v244, 0x7f, v243
	v_min_u32_e32 v245, 0x9f, v243
	v_lshl_add_u32 v244, v244, 2, s98
	v_lshl_add_u32 v245, v245, 2, s99
	ds_read_b32 v116, v244
	ds_read_b32 v100, v245
	v_add_u32_e32 v243, -1, v67
	v_min_u32_e32 v244, 0x7f, v243
	v_min_u32_e32 v245, 0x9f, v243
	v_lshl_add_u32 v244, v244, 2, s98
	v_lshl_add_u32 v245, v245, 2, s99
	ds_read_b32 v117, v244
	ds_read_b32 v101, v245
	v_add_u32_e32 v243, -2, v67
	v_min_u32_e32 v244, 0x7f, v243
	v_min_u32_e32 v245, 0x9f, v243
	v_lshl_add_u32 v244, v244, 2, s98
	v_lshl_add_u32 v245, v245, 2, s99
	ds_read_b32 v118, v244
	ds_read_b32 v102, v245
	v_add_u32_e32 v243, -3, v67
	v_min_u32_e32 v244, 0x7f, v243
	v_min_u32_e32 v245, 0x9f, v243
	v_lshl_add_u32 v244, v244, 2, s98
	v_lshl_add_u32 v245, v245, 2, s99
	ds_read_b32 v119, v244
	ds_read_b32 v103, v245
	v_add_u32_e32 v243, -8, v67
	v_min_u32_e32 v244, 0x7f, v243
	v_min_u32_e32 v245, 0x9f, v243
	v_lshl_add_u32 v244, v244, 2, s98
	v_lshl_add_u32 v245, v245, 2, s99
	ds_read_b32 v120, v244
	ds_read_b32 v104, v245
	v_add_u32_e32 v243, -9, v67
	v_min_u32_e32 v244, 0x7f, v243
	v_min_u32_e32 v245, 0x9f, v243
	v_lshl_add_u32 v244, v244, 2, s98
	v_lshl_add_u32 v245, v245, 2, s99
	ds_read_b32 v121, v244
	ds_read_b32 v105, v245
	v_add_u32_e32 v243, -10, v67
	v_min_u32_e32 v244, 0x7f, v243
	v_min_u32_e32 v245, 0x9f, v243
	v_lshl_add_u32 v244, v244, 2, s98
	v_lshl_add_u32 v245, v245, 2, s99
	ds_read_b32 v122, v244
	ds_read_b32 v106, v245
	v_add_u32_e32 v243, -11, v67
	v_min_u32_e32 v244, 0x7f, v243
	v_min_u32_e32 v245, 0x9f, v243
	v_lshl_add_u32 v244, v244, 2, s98
	v_lshl_add_u32 v245, v245, 2, s99
	ds_read_b32 v123, v244
	ds_read_b32 v107, v245
	v_add_u32_e32 v243, -16, v67
	v_min_u32_e32 v244, 0x7f, v243
	v_min_u32_e32 v245, 0x9f, v243
	v_lshl_add_u32 v244, v244, 2, s98
	v_lshl_add_u32 v245, v245, 2, s99
	ds_read_b32 v124, v244
	ds_read_b32 v108, v245
	v_add_u32_e32 v243, 0xffffffef, v67
	v_min_u32_e32 v244, 0x7f, v243
	v_min_u32_e32 v245, 0x9f, v243
	v_lshl_add_u32 v244, v244, 2, s98
	v_lshl_add_u32 v245, v245, 2, s99
	ds_read_b32 v125, v244
	ds_read_b32 v109, v245
	v_add_u32_e32 v243, 0xffffffee, v67
	v_min_u32_e32 v244, 0x7f, v243
	v_min_u32_e32 v245, 0x9f, v243
	v_lshl_add_u32 v244, v244, 2, s98
	v_lshl_add_u32 v245, v245, 2, s99
	ds_read_b32 v126, v244
	ds_read_b32 v110, v245
	v_add_u32_e32 v243, 0xffffffed, v67
	v_min_u32_e32 v244, 0x7f, v243
	v_min_u32_e32 v245, 0x9f, v243
	v_lshl_add_u32 v244, v244, 2, s98
	v_lshl_add_u32 v245, v245, 2, s99
	ds_read_b32 v127, v244
	ds_read_b32 v111, v245
	v_add_u32_e32 v243, 0xffffffe8, v67
	v_min_u32_e32 v244, 0x7f, v243
	v_min_u32_e32 v245, 0x9f, v243
	v_lshl_add_u32 v244, v244, 2, s98
	v_lshl_add_u32 v245, v245, 2, s99
	ds_read_b32 v128, v244
	ds_read_b32 v112, v245
	v_add_u32_e32 v243, 0xffffffe7, v67
	v_min_u32_e32 v244, 0x7f, v243
	v_min_u32_e32 v245, 0x9f, v243
	v_lshl_add_u32 v244, v244, 2, s98
	v_lshl_add_u32 v245, v245, 2, s99
	ds_read_b32 v129, v244
	ds_read_b32 v113, v245
	v_add_u32_e32 v243, 0xffffffe6, v67
	v_min_u32_e32 v244, 0x7f, v243
	v_min_u32_e32 v245, 0x9f, v243
	v_lshl_add_u32 v244, v244, 2, s98
	v_lshl_add_u32 v245, v245, 2, s99
	ds_read_b32 v130, v244
	ds_read_b32 v114, v245
	v_add_u32_e32 v243, 0xffffffe5, v67
	v_min_u32_e32 v244, 0x7f, v243
	v_min_u32_e32 v245, 0x9f, v243
	v_lshl_add_u32 v244, v244, 2, s98
	v_lshl_add_u32 v245, v245, 2, s99
	ds_read_b32 v131, v244
	ds_read_b32 v115, v245
	s_waitcnt lgkmcnt(0)
	v_add_u32_e32 v243, 0, v67
	v_add_f32_e32 v116, v84, v116
	v_cmp_lt_i32_e32 vcc, -1, v243
	v_cndmask_b32_e32 v116, v246, v116, vcc
	v_add_f32_e32 v100, v68, v100
	v_cmp_lt_i32_e32 vcc, 31, v243
	v_cndmask_b32_e32 v100, v246, v100, vcc
	v_add_u32_e32 v243, -1, v67
	v_add_f32_e32 v117, v85, v117
	v_cmp_lt_i32_e32 vcc, -1, v243
	v_cndmask_b32_e32 v117, v246, v117, vcc
	v_add_f32_e32 v101, v69, v101
	v_cmp_lt_i32_e32 vcc, 31, v243
	v_cndmask_b32_e32 v101, v246, v101, vcc
	v_add_u32_e32 v243, -2, v67
	v_add_f32_e32 v118, v86, v118
	v_cmp_lt_i32_e32 vcc, -1, v243
	v_cndmask_b32_e32 v118, v246, v118, vcc
	v_add_f32_e32 v102, v70, v102
	v_cmp_lt_i32_e32 vcc, 31, v243
	v_cndmask_b32_e32 v102, v246, v102, vcc
	v_add_u32_e32 v243, -3, v67
	v_add_f32_e32 v119, v87, v119
	v_cmp_lt_i32_e32 vcc, -1, v243
	v_cndmask_b32_e32 v119, v246, v119, vcc
	v_add_f32_e32 v103, v71, v103
	v_cmp_lt_i32_e32 vcc, 31, v243
	v_cndmask_b32_e32 v103, v246, v103, vcc
	v_add_u32_e32 v243, -8, v67
	v_add_f32_e32 v120, v88, v120
	v_cmp_lt_i32_e32 vcc, -1, v243
	v_cndmask_b32_e32 v120, v246, v120, vcc
	v_add_f32_e32 v104, v72, v104
	v_cmp_lt_i32_e32 vcc, 31, v243
	v_cndmask_b32_e32 v104, v246, v104, vcc
	v_add_u32_e32 v243, -9, v67
	v_add_f32_e32 v121, v89, v121
	v_cmp_lt_i32_e32 vcc, -1, v243
	v_cndmask_b32_e32 v121, v246, v121, vcc
	v_add_f32_e32 v105, v73, v105
	v_cmp_lt_i32_e32 vcc, 31, v243
	v_cndmask_b32_e32 v105, v246, v105, vcc
	v_add_u32_e32 v243, -10, v67
	v_add_f32_e32 v122, v90, v122
	v_cmp_lt_i32_e32 vcc, -1, v243
	v_cndmask_b32_e32 v122, v246, v122, vcc
	v_add_f32_e32 v106, v74, v106
	v_cmp_lt_i32_e32 vcc, 31, v243
	v_cndmask_b32_e32 v106, v246, v106, vcc
	v_add_u32_e32 v243, -11, v67
	v_add_f32_e32 v123, v91, v123
	v_cmp_lt_i32_e32 vcc, -1, v243
	v_cndmask_b32_e32 v123, v246, v123, vcc
	v_add_f32_e32 v107, v75, v107
	v_cmp_lt_i32_e32 vcc, 31, v243
	v_cndmask_b32_e32 v107, v246, v107, vcc
	v_add_u32_e32 v243, -16, v67
	v_add_f32_e32 v124, v92, v124
	v_cmp_lt_i32_e32 vcc, -1, v243
	v_cndmask_b32_e32 v124, v246, v124, vcc
	v_add_f32_e32 v108, v76, v108
	v_cmp_lt_i32_e32 vcc, 31, v243
	v_cndmask_b32_e32 v108, v246, v108, vcc
	v_add_u32_e32 v243, 0xffffffef, v67
	v_add_f32_e32 v125, v93, v125
	v_cmp_lt_i32_e32 vcc, -1, v243
	v_cndmask_b32_e32 v125, v246, v125, vcc
	v_add_f32_e32 v109, v77, v109
	v_cmp_lt_i32_e32 vcc, 31, v243
	v_cndmask_b32_e32 v109, v246, v109, vcc
	v_add_u32_e32 v243, 0xffffffee, v67
	v_add_f32_e32 v126, v94, v126
	v_cmp_lt_i32_e32 vcc, -1, v243
	v_cndmask_b32_e32 v126, v246, v126, vcc
	v_add_f32_e32 v110, v78, v110
	v_cmp_lt_i32_e32 vcc, 31, v243
	v_cndmask_b32_e32 v110, v246, v110, vcc
	v_add_u32_e32 v243, 0xffffffed, v67
	v_add_f32_e32 v127, v95, v127
	v_cmp_lt_i32_e32 vcc, -1, v243
	v_cndmask_b32_e32 v127, v246, v127, vcc
	v_add_f32_e32 v111, v79, v111
	v_cmp_lt_i32_e32 vcc, 31, v243
	v_cndmask_b32_e32 v111, v246, v111, vcc
	v_add_u32_e32 v243, 0xffffffe8, v67
	v_add_f32_e32 v128, v96, v128
	v_cmp_lt_i32_e32 vcc, -1, v243
	v_cndmask_b32_e32 v128, v246, v128, vcc
	v_add_f32_e32 v112, v80, v112
	v_cmp_lt_i32_e32 vcc, 31, v243
	v_cndmask_b32_e32 v112, v246, v112, vcc
	v_add_u32_e32 v243, 0xffffffe7, v67
	v_add_f32_e32 v129, v97, v129
	v_cmp_lt_i32_e32 vcc, -1, v243
	v_cndmask_b32_e32 v129, v246, v129, vcc
	v_add_f32_e32 v113, v81, v113
	v_cmp_lt_i32_e32 vcc, 31, v243
	v_cndmask_b32_e32 v113, v246, v113, vcc
	v_add_u32_e32 v243, 0xffffffe6, v67
	v_add_f32_e32 v130, v98, v130
	v_cmp_lt_i32_e32 vcc, -1, v243
	v_cndmask_b32_e32 v130, v246, v130, vcc
	v_add_f32_e32 v114, v82, v114
	v_cmp_lt_i32_e32 vcc, 31, v243
	v_cndmask_b32_e32 v114, v246, v114, vcc
	v_add_u32_e32 v243, 0xffffffe5, v67
	v_add_f32_e32 v131, v99, v131
	v_cmp_lt_i32_e32 vcc, -1, v243
	v_cndmask_b32_e32 v131, v246, v131, vcc
	v_add_f32_e32 v115, v83, v115
	v_cmp_lt_i32_e32 vcc, 31, v243
	v_cndmask_b32_e32 v115, v246, v115, vcc

.LBB0_2416:
	ds_read_b128 v[68:71], v234 offset:37888
	ds_read_b128 v[100:103], v234 offset:37920
	ds_read_b128 v[72:75], v234 offset:46592
	ds_read_b128 v[104:107], v234 offset:46624
	ds_read_b128 v[108:111], v234 offset:37952
	ds_read_b128 v[112:115], v234 offset:37984
	ds_read_b128 v[116:119], v234 offset:46656
	ds_read_b128 v[120:123], v234 offset:46688
	s_add_i32 s12, s68, -2
	s_waitcnt lgkmcnt(7)
	v_mfma_f32_32x32x16_bf16 v[84:99], v[68:71], v[140:143], 0
	ds_read_b64_tr_b16 v[176:177], v235 offset:55296
	ds_read_b64_tr_b16 v[172:173], v235 offset:55360
	ds_read_b64_tr_b16 v[168:169], v235 offset:55424
	ds_read_b64_tr_b16 v[164:165], v235 offset:55488
	ds_read_b64_tr_b16 v[178:179], v235 offset:57856
	ds_read_b64_tr_b16 v[174:175], v235 offset:57920
	ds_read_b64_tr_b16 v[170:171], v235 offset:57984
	ds_read_b64_tr_b16 v[166:167], v235 offset:58048
	s_waitcnt lgkmcnt(13)
	v_mfma_f32_32x32x16_bf16 v[68:83], v[72:75], v[140:143], 0
	v_mfma_f32_32x32x16_bf16 v[84:99], v[100:103], v[132:135], v[84:99]
	s_waitcnt lgkmcnt(12)
	v_mfma_f32_32x32x16_bf16 v[68:83], v[104:107], v[132:135], v[68:83]
	s_waitcnt lgkmcnt(11)
	v_mfma_f32_32x32x16_bf16 v[84:99], v[108:111], v[136:139], v[84:99]
	s_waitcnt lgkmcnt(9)
	v_mfma_f32_32x32x16_bf16 v[68:83], v[116:119], v[136:139], v[68:83]
	v_mfma_f32_32x32x16_bf16 v[84:99], v[112:115], v[144:147], v[84:99]
	s_waitcnt lgkmcnt(8)
	v_mfma_f32_32x32x16_bf16 v[68:83], v[120:123], v[144:147], v[68:83]
	s_cmp_lt_i32 s12, s67
	s_cbranch_scc1 .LBB0_2482
	s_mov_b32 s98, 0x12800
	s_mov_b32 s99, 0x12780
	v_mov_b32_e32 v246, 0xf149f2ca
	v_add_u32_e32 v243, 0xffffffc0, v67
	v_min_u32_e32 v244, 0x7f, v243
	v_min_u32_e32 v245, 0x9f, v243
	v_lshl_add_u32 v244, v244, 2, s98
	v_lshl_add_u32 v245, v245, 2, s99
	ds_read_b32 v116, v244
	ds_read_b32 v100, v245
	v_add_u32_e32 v243, 0xffffffbf, v67
	v_min_u32_e32 v244, 0x7f, v243
	v_min_u32_e32 v245, 0x9f, v243
	v_lshl_add_u32 v244, v244, 2, s98
	v_lshl_add_u32 v245, v245, 2, s99
	ds_read_b32 v117, v244
	ds_read_b32 v101, v245
	v_add_u32_e32 v243, 0xffffffbe, v67
	v_min_u32_e32 v244, 0x7f, v243
	v_min_u32_e32 v245, 0x9f, v243
	v_lshl_add_u32 v244, v244, 2, s98
	v_lshl_add_u32 v245, v245, 2, s99
	ds_read_b32 v118, v244
	ds_read_b32 v102, v245
	v_add_u32_e32 v243, 0xffffffbd, v67
	v_min_u32_e32 v244, 0x7f, v243
	v_min_u32_e32 v245, 0x9f, v243
	v_lshl_add_u32 v244, v244, 2, s98
	v_lshl_add_u32 v245, v245, 2, s99
	ds_read_b32 v119, v244
	ds_read_b32 v103, v245
	v_add_u32_e32 v243, 0xffffffb8, v67
	v_min_u32_e32 v244, 0x7f, v243
	v_min_u32_e32 v245, 0x9f, v243
	v_lshl_add_u32 v244, v244, 2, s98
	v_lshl_add_u32 v245, v245, 2, s99
	ds_read_b32 v120, v244
	ds_read_b32 v104, v245
	v_add_u32_e32 v243, 0xffffffb7, v67
	v_min_u32_e32 v244, 0x7f, v243
	v_min_u32_e32 v245, 0x9f, v243
	v_lshl_add_u32 v244, v244, 2, s98
	v_lshl_add_u32 v245, v245, 2, s99
	ds_read_b32 v121, v244
	ds_read_b32 v105, v245
	v_add_u32_e32 v243, 0xffffffb6, v67
	v_min_u32_e32 v244, 0x7f, v243
	v_min_u32_e32 v245, 0x9f, v243
	v_lshl_add_u32 v244, v244, 2, s98
	v_lshl_add_u32 v245, v245, 2, s99
	ds_read_b32 v122, v244
	ds_read_b32 v106, v245
	v_add_u32_e32 v243, 0xffffffb5, v67
	v_min_u32_e32 v244, 0x7f, v243
	v_min_u32_e32 v245, 0x9f, v243
	v_lshl_add_u32 v244, v244, 2, s98
	v_lshl_add_u32 v245, v245, 2, s99
	ds_read_b32 v123, v244
	ds_read_b32 v107, v245
	v_add_u32_e32 v243, 0xffffffb0, v67
	v_min_u32_e32 v244, 0x7f, v243
	v_min_u32_e32 v245, 0x9f, v243
	v_lshl_add_u32 v244, v244, 2, s98
	v_lshl_add_u32 v245, v245, 2, s99
	ds_read_b32 v124, v244
	ds_read_b32 v108, v245
	v_add_u32_e32 v243, 0xffffffaf, v67
	v_min_u32_e32 v244, 0x7f, v243
	v_min_u32_e32 v245, 0x9f, v243
	v_lshl_add_u32 v244, v244, 2, s98
	v_lshl_add_u32 v245, v245, 2, s99
	ds_read_b32 v125, v244
	ds_read_b32 v109, v245
	v_add_u32_e32 v243, 0xffffffae, v67
	v_min_u32_e32 v244, 0x7f, v243
	v_min_u32_e32 v245, 0x9f, v243
	v_lshl_add_u32 v244, v244, 2, s98
	v_lshl_add_u32 v245, v245, 2, s99
	ds_read_b32 v126, v244
	ds_read_b32 v110, v245
	v_add_u32_e32 v243, 0xffffffad, v67
	v_min_u32_e32 v244, 0x7f, v243
	v_min_u32_e32 v245, 0x9f, v243
	v_lshl_add_u32 v244, v244, 2, s98
	v_lshl_add_u32 v245, v245, 2, s99
	ds_read_b32 v127, v244
	ds_read_b32 v111, v245
	v_add_u32_e32 v243, 0xffffffa8, v67
	v_min_u32_e32 v244, 0x7f, v243
	v_min_u32_e32 v245, 0x9f, v243
	v_lshl_add_u32 v244, v244, 2, s98
	v_lshl_add_u32 v245, v245, 2, s99
	ds_read_b32 v128, v244
	ds_read_b32 v112, v245
	v_add_u32_e32 v243, 0xffffffa7, v67
	v_min_u32_e32 v244, 0x7f, v243
	v_min_u32_e32 v245, 0x9f, v243
	v_lshl_add_u32 v244, v244, 2, s98
	v_lshl_add_u32 v245, v245, 2, s99
	ds_read_b32 v129, v244
	ds_read_b32 v113, v245
	v_add_u32_e32 v243, 0xffffffa6, v67
	v_min_u32_e32 v244, 0x7f, v243
	v_min_u32_e32 v245, 0x9f, v243
	v_lshl_add_u32 v244, v244, 2, s98
	v_lshl_add_u32 v245, v245, 2, s99
	ds_read_b32 v130, v244
	ds_read_b32 v114, v245
	v_add_u32_e32 v243, 0xffffffa5, v67
	v_min_u32_e32 v244, 0x7f, v243
	v_min_u32_e32 v245, 0x9f, v243
	v_lshl_add_u32 v244, v244, 2, s98
	v_lshl_add_u32 v245, v245, 2, s99
	ds_read_b32 v131, v244
	ds_read_b32 v115, v245
	s_waitcnt lgkmcnt(0)
	v_add_u32_e32 v243, 0xffffffc0, v67
	v_add_f32_e32 v116, v84, v116
	v_cmp_lt_i32_e32 vcc, -1, v243
	v_cndmask_b32_e32 v116, v246, v116, vcc
	v_add_f32_e32 v100, v68, v100
	v_cmp_lt_i32_e32 vcc, 31, v243
	v_cndmask_b32_e32 v100, v246, v100, vcc
	v_add_u32_e32 v243, 0xffffffbf, v67
	v_add_f32_e32 v117, v85, v117
	v_cmp_lt_i32_e32 vcc, -1, v243
	v_cndmask_b32_e32 v117, v246, v117, vcc
	v_add_f32_e32 v101, v69, v101
	v_cmp_lt_i32_e32 vcc, 31, v243
	v_cndmask_b32_e32 v101, v246, v101, vcc
	v_add_u32_e32 v243, 0xffffffbe, v67
	v_add_f32_e32 v118, v86, v118
	v_cmp_lt_i32_e32 vcc, -1, v243
	v_cndmask_b32_e32 v118, v246, v118, vcc
	v_add_f32_e32 v102, v70, v102
	v_cmp_lt_i32_e32 vcc, 31, v243
	v_cndmask_b32_e32 v102, v246, v102, vcc
	v_add_u32_e32 v243, 0xffffffbd, v67
	v_add_f32_e32 v119, v87, v119
	v_cmp_lt_i32_e32 vcc, -1, v243
	v_cndmask_b32_e32 v119, v246, v119, vcc
	v_add_f32_e32 v103, v71, v103
	v_cmp_lt_i32_e32 vcc, 31, v243
	v_cndmask_b32_e32 v103, v246, v103, vcc
	v_add_u32_e32 v243, 0xffffffb8, v67
	v_add_f32_e32 v120, v88, v120
	v_cmp_lt_i32_e32 vcc, -1, v243
	v_cndmask_b32_e32 v120, v246, v120, vcc
	v_add_f32_e32 v104, v72, v104
	v_cmp_lt_i32_e32 vcc, 31, v243
	v_cndmask_b32_e32 v104, v246, v104, vcc
	v_add_u32_e32 v243, 0xffffffb7, v67
	v_add_f32_e32 v121, v89, v121
	v_cmp_lt_i32_e32 vcc, -1, v243
	v_cndmask_b32_e32 v121, v246, v121, vcc
	v_add_f32_e32 v105, v73, v105
	v_cmp_lt_i32_e32 vcc, 31, v243
	v_cndmask_b32_e32 v105, v246, v105, vcc
	v_add_u32_e32 v243, 0xffffffb6, v67
	v_add_f32_e32 v122, v90, v122
	v_cmp_lt_i32_e32 vcc, -1, v243
	v_cndmask_b32_e32 v122, v246, v122, vcc
	v_add_f32_e32 v106, v74, v106
	v_cmp_lt_i32_e32 vcc, 31, v243
	v_cndmask_b32_e32 v106, v246, v106, vcc
	v_add_u32_e32 v243, 0xffffffb5, v67
	v_add_f32_e32 v123, v91, v123
	v_cmp_lt_i32_e32 vcc, -1, v243
	v_cndmask_b32_e32 v123, v246, v123, vcc
	v_add_f32_e32 v107, v75, v107
	v_cmp_lt_i32_e32 vcc, 31, v243
	v_cndmask_b32_e32 v107, v246, v107, vcc
	v_add_u32_e32 v243, 0xffffffb0, v67
	v_add_f32_e32 v124, v92, v124
	v_cmp_lt_i32_e32 vcc, -1, v243
	v_cndmask_b32_e32 v124, v246, v124, vcc
	v_add_f32_e32 v108, v76, v108
	v_cmp_lt_i32_e32 vcc, 31, v243
	v_cndmask_b32_e32 v108, v246, v108, vcc
	v_add_u32_e32 v243, 0xffffffaf, v67
	v_add_f32_e32 v125, v93, v125
	v_cmp_lt_i32_e32 vcc, -1, v243
	v_cndmask_b32_e32 v125, v246, v125, vcc
	v_add_f32_e32 v109, v77, v109
	v_cmp_lt_i32_e32 vcc, 31, v243
	v_cndmask_b32_e32 v109, v246, v109, vcc
	v_add_u32_e32 v243, 0xffffffae, v67
	v_add_f32_e32 v126, v94, v126
	v_cmp_lt_i32_e32 vcc, -1, v243
	v_cndmask_b32_e32 v126, v246, v126, vcc
	v_add_f32_e32 v110, v78, v110
	v_cmp_lt_i32_e32 vcc, 31, v243
	v_cndmask_b32_e32 v110, v246, v110, vcc
	v_add_u32_e32 v243, 0xffffffad, v67
	v_add_f32_e32 v127, v95, v127
	v_cmp_lt_i32_e32 vcc, -1, v243
	v_cndmask_b32_e32 v127, v246, v127, vcc
	v_add_f32_e32 v111, v79, v111
	v_cmp_lt_i32_e32 vcc, 31, v243
	v_cndmask_b32_e32 v111, v246, v111, vcc
	v_add_u32_e32 v243, 0xffffffa8, v67
	v_add_f32_e32 v128, v96, v128
	v_cmp_lt_i32_e32 vcc, -1, v243
	v_cndmask_b32_e32 v128, v246, v128, vcc
	v_add_f32_e32 v112, v80, v112
	v_cmp_lt_i32_e32 vcc, 31, v243
	v_cndmask_b32_e32 v112, v246, v112, vcc
	v_add_u32_e32 v243, 0xffffffa7, v67
	v_add_f32_e32 v129, v97, v129
	v_cmp_lt_i32_e32 vcc, -1, v243
	v_cndmask_b32_e32 v129, v246, v129, vcc
	v_add_f32_e32 v113, v81, v113
	v_cmp_lt_i32_e32 vcc, 31, v243
	v_cndmask_b32_e32 v113, v246, v113, vcc
	v_add_u32_e32 v243, 0xffffffa6, v67
	v_add_f32_e32 v130, v98, v130
	v_cmp_lt_i32_e32 vcc, -1, v243
	v_cndmask_b32_e32 v130, v246, v130, vcc
	v_add_f32_e32 v114, v82, v114
	v_cmp_lt_i32_e32 vcc, 31, v243
	v_cndmask_b32_e32 v114, v246, v114, vcc
	v_add_u32_e32 v243, 0xffffffa5, v67
	v_add_f32_e32 v131, v99, v131
	v_cmp_lt_i32_e32 vcc, -1, v243
	v_cndmask_b32_e32 v131, v246, v131, vcc
	v_add_f32_e32 v115, v83, v115
	v_cmp_lt_i32_e32 vcc, 31, v243
	v_cndmask_b32_e32 v115, v246, v115, vcc

	.amdhsa_kernel _Z10hybrid_fwd4Args
		.amdhsa_group_segment_fixed_size 0
		.amdhsa_private_segment_fixed_size 0
		.amdhsa_kernarg_size 440
		.amdhsa_user_sgpr_count 2
		.amdhsa_user_sgpr_dispatch_ptr 0
		.amdhsa_user_sgpr_queue_ptr 0
		.amdhsa_user_sgpr_kernarg_segment_ptr 1
		.amdhsa_user_sgpr_dispatch_id 0
		.amdhsa_user_sgpr_kernarg_preload_length 0
		.amdhsa_user_sgpr_kernarg_preload_offset 0
		.amdhsa_user_sgpr_private_segment_size 0
		.amdhsa_uses_dynamic_stack 0
		.amdhsa_enable_private_segment 0
		.amdhsa_system_sgpr_workgroup_id_x 1
		.amdhsa_system_sgpr_workgroup_id_y 0
		.amdhsa_system_sgpr_workgroup_id_z 0
		.amdhsa_system_sgpr_workgroup_info 0
		.amdhsa_system_vgpr_workitem_id 0
		.amdhsa_next_free_vgpr 251
		.amdhsa_next_free_sgpr 100
		.amdhsa_accum_offset 252
		.amdhsa_reserve_vcc 1
		.amdhsa_float_round_mode_32 0
		.amdhsa_float_round_mode_16_64 0
		.amdhsa_float_denorm_mode_32 3
		.amdhsa_float_denorm_mode_16_64 3
		.amdhsa_dx10_clamp 1
		.amdhsa_ieee_mode 1
		.amdhsa_fp16_overflow 0
		.amdhsa_tg_split 0
		.amdhsa_exception_fp_ieee_invalid_op 0
		.amdhsa_exception_fp_denorm_src 0
		.amdhsa_exception_fp_ieee_div_zero 0
		.amdhsa_exception_fp_ieee_overflow 0
		.amdhsa_exception_fp_ieee_underflow 0
		.amdhsa_exception_fp_ieee_inexact 0
		.amdhsa_exception_int_div_zero 0
	.end_amdhsa_kernel

amdhsa.kernels:
  - .agpr_count:     0
    .args:
      - .offset:         0
        .size:           184
        .value_kind:     by_value
      - .offset:         184
        .size:           4
        .value_kind:     hidden_block_count_x
      - .offset:         188
        .size:           4
        .value_kind:     hidden_block_count_y
      - .offset:         192
        .size:           4
        .value_kind:     hidden_block_count_z
      - .offset:         196
        .size:           2
        .value_kind:     hidden_group_size_x
      - .offset:         198
        .size:           2
        .value_kind:     hidden_group_size_y
      - .offset:         200
        .size:           2
        .value_kind:     hidden_group_size_z
      - .offset:         202
        .size:           2
        .value_kind:     hidden_remainder_x
      - .offset:         204
        .size:           2
        .value_kind:     hidden_remainder_y
      - .offset:         206
        .size:           2
        .value_kind:     hidden_remainder_z
      - .offset:         224
        .size:           8
        .value_kind:     hidden_global_offset_x
      - .offset:         232
        .size:           8
        .value_kind:     hidden_global_offset_y
      - .offset:         240
        .size:           8
        .value_kind:     hidden_global_offset_z
      - .offset:         248
        .size:           2
        .value_kind:     hidden_grid_dims
      - .offset:         304
        .size:           4
        .value_kind:     hidden_dynamic_lds_size
    .group_segment_fixed_size: 0
    .kernarg_segment_align: 8
    .kernarg_segment_size: 440
    .language:       OpenCL C
    .language_version:
      - 2
      - 0
    .max_flat_workgroup_size: 512
    .name:           _Z10hybrid_fwd4Args
    .private_segment_fixed_size: 0
    .sgpr_count:     106
    .sgpr_spill_count: 34
    .symbol:         _Z10hybrid_fwd4Args.kd
    .uniform_work_group_size: 1
    .uses_dynamic_stack: false
    .vgpr_count:     251
    .vgpr_spill_count: 0
    .wavefront_size: 64
